# prologue adaLN GEMV: 32 weight-row loads in flight per wave with counted vmcnt (was 4 loads then vmcnt(0) per step)
# speedup vs baseline: 1.0036x; 1.0017x over previous
;     __device__ __forceinline__ const float* in(int i) const { return (const float*)(__attribute__((address_space(1))) const float*)ld64(i); }
; __device__ __forceinline__ void prologue(const Ctx& a, LAS unsigned char* lds, int wave_s) {
;     ...
;     for (int item = bid; item < 384; item += nblk) {
;         const int layer = item / 96, n0 = (item % 96) * 64;
;         const float* W = a.in(4) + (size_t)layer * 1024 * 6144 + n0 + lane;
;         float acc[10];
; #pragma unroll
;         for (int b = 0; b < 10; ++b) acc[b] = 0.f;
;         for (int k = wave * 128; k < wave * 128 + 128; ++k) { const float w = W[(size_t)k * 6144];
; #pragma unroll
;             for (int b = 0; b < 10; ++b) acc[b] += cact[b * 1024 + k] * w; }
.LBB0_27:
	v_lshl_add_u64 v[26:27], v[14:15], 0, s[10:11]
	s_add_u32 s10, s10, 0x6000
	s_addc_u32 s11, s11, 0
	global_load_dword v100, v[26:27], off
	v_lshl_add_u64 v[26:27], v[14:15], 0, s[10:11]
	s_add_u32 s10, s10, 0x6000
	s_addc_u32 s11, s11, 0
	global_load_dword v101, v[26:27], off
	v_lshl_add_u64 v[26:27], v[14:15], 0, s[10:11]
	s_add_u32 s10, s10, 0x6000
	s_addc_u32 s11, s11, 0
	global_load_dword v102, v[26:27], off
	v_lshl_add_u64 v[26:27], v[14:15], 0, s[10:11]
	s_add_u32 s10, s10, 0x6000
	s_addc_u32 s11, s11, 0
	global_load_dword v103, v[26:27], off
	v_lshl_add_u64 v[26:27], v[14:15], 0, s[10:11]
	s_add_u32 s10, s10, 0x6000
	s_addc_u32 s11, s11, 0
	global_load_dword v104, v[26:27], off
	v_lshl_add_u64 v[26:27], v[14:15], 0, s[10:11]
	s_add_u32 s10, s10, 0x6000
	s_addc_u32 s11, s11, 0
	global_load_dword v105, v[26:27], off
	v_lshl_add_u64 v[26:27], v[14:15], 0, s[10:11]
	s_add_u32 s10, s10, 0x6000
	s_addc_u32 s11, s11, 0
	global_load_dword v106, v[26:27], off
	v_lshl_add_u64 v[26:27], v[14:15], 0, s[10:11]
	s_add_u32 s10, s10, 0x6000
	s_addc_u32 s11, s11, 0
	global_load_dword v107, v[26:27], off
	v_lshl_add_u64 v[26:27], v[14:15], 0, s[10:11]
	s_add_u32 s10, s10, 0x6000
	s_addc_u32 s11, s11, 0
	global_load_dword v108, v[26:27], off
	v_lshl_add_u64 v[26:27], v[14:15], 0, s[10:11]
	s_add_u32 s10, s10, 0x6000
	s_addc_u32 s11, s11, 0
	global_load_dword v109, v[26:27], off
	v_lshl_add_u64 v[26:27], v[14:15], 0, s[10:11]
	s_add_u32 s10, s10, 0x6000
	s_addc_u32 s11, s11, 0
	global_load_dword v110, v[26:27], off
	v_lshl_add_u64 v[26:27], v[14:15], 0, s[10:11]
	s_add_u32 s10, s10, 0x6000
	s_addc_u32 s11, s11, 0
	global_load_dword v111, v[26:27], off
	v_lshl_add_u64 v[26:27], v[14:15], 0, s[10:11]
	s_add_u32 s10, s10, 0x6000
	s_addc_u32 s11, s11, 0
	global_load_dword v112, v[26:27], off
	v_lshl_add_u64 v[26:27], v[14:15], 0, s[10:11]
	s_add_u32 s10, s10, 0x6000
	s_addc_u32 s11, s11, 0
	global_load_dword v113, v[26:27], off
	v_lshl_add_u64 v[26:27], v[14:15], 0, s[10:11]
	s_add_u32 s10, s10, 0x6000
	s_addc_u32 s11, s11, 0
	global_load_dword v114, v[26:27], off
	v_lshl_add_u64 v[26:27], v[14:15], 0, s[10:11]
	s_add_u32 s10, s10, 0x6000
	s_addc_u32 s11, s11, 0
	global_load_dword v115, v[26:27], off
	v_lshl_add_u64 v[26:27], v[14:15], 0, s[10:11]
	s_add_u32 s10, s10, 0x6000
	s_addc_u32 s11, s11, 0
	global_load_dword v116, v[26:27], off
	v_lshl_add_u64 v[26:27], v[14:15], 0, s[10:11]
	s_add_u32 s10, s10, 0x6000
	s_addc_u32 s11, s11, 0
	global_load_dword v117, v[26:27], off
	v_lshl_add_u64 v[26:27], v[14:15], 0, s[10:11]
	s_add_u32 s10, s10, 0x6000
	s_addc_u32 s11, s11, 0
	global_load_dword v118, v[26:27], off
	v_lshl_add_u64 v[26:27], v[14:15], 0, s[10:11]
	s_add_u32 s10, s10, 0x6000
	s_addc_u32 s11, s11, 0
	global_load_dword v119, v[26:27], off
	v_lshl_add_u64 v[26:27], v[14:15], 0, s[10:11]
	s_add_u32 s10, s10, 0x6000
	s_addc_u32 s11, s11, 0
	global_load_dword v120, v[26:27], off
	v_lshl_add_u64 v[26:27], v[14:15], 0, s[10:11]
	s_add_u32 s10, s10, 0x6000
	s_addc_u32 s11, s11, 0
	global_load_dword v121, v[26:27], off
	v_lshl_add_u64 v[26:27], v[14:15], 0, s[10:11]
	s_add_u32 s10, s10, 0x6000
	s_addc_u32 s11, s11, 0
	global_load_dword v122, v[26:27], off
	v_lshl_add_u64 v[26:27], v[14:15], 0, s[10:11]
	s_add_u32 s10, s10, 0x6000
	s_addc_u32 s11, s11, 0
	global_load_dword v123, v[26:27], off
	v_lshl_add_u64 v[26:27], v[14:15], 0, s[10:11]
	s_add_u32 s10, s10, 0x6000
	s_addc_u32 s11, s11, 0
	global_load_dword v124, v[26:27], off
	v_lshl_add_u64 v[26:27], v[14:15], 0, s[10:11]
	s_add_u32 s10, s10, 0x6000
	s_addc_u32 s11, s11, 0
	global_load_dword v125, v[26:27], off
	v_lshl_add_u64 v[26:27], v[14:15], 0, s[10:11]
	s_add_u32 s10, s10, 0x6000
	s_addc_u32 s11, s11, 0
	global_load_dword v126, v[26:27], off
	v_lshl_add_u64 v[26:27], v[14:15], 0, s[10:11]
	s_add_u32 s10, s10, 0x6000
	s_addc_u32 s11, s11, 0
	global_load_dword v127, v[26:27], off
	v_lshl_add_u64 v[26:27], v[14:15], 0, s[10:11]
	s_add_u32 s10, s10, 0x6000
	s_addc_u32 s11, s11, 0
	global_load_dword v128, v[26:27], off
	v_lshl_add_u64 v[26:27], v[14:15], 0, s[10:11]
	s_add_u32 s10, s10, 0x6000
	s_addc_u32 s11, s11, 0
	global_load_dword v129, v[26:27], off
	v_lshl_add_u64 v[26:27], v[14:15], 0, s[10:11]
	s_add_u32 s10, s10, 0x6000
	s_addc_u32 s11, s11, 0
	global_load_dword v130, v[26:27], off
	v_lshl_add_u64 v[26:27], v[14:15], 0, s[10:11]
	s_add_u32 s10, s10, 0x6000
	s_addc_u32 s11, s11, 0
	global_load_dword v131, v[26:27], off
	v_mov_b32_e32 v28, s20
	s_add_i32 s20, s20, 16
	ds_read_b128 v[30:33], v28
	ds_read_b128 v[34:37], v28 offset:4096
	ds_read_b128 v[38:41], v28 offset:8192
	ds_read_b128 v[42:45], v28 offset:12288
	ds_read_b128 v[46:49], v28 offset:16384
	ds_read_b128 v[50:53], v28 offset:20480
	ds_read_b128 v[54:57], v28 offset:24576
	ds_read_b128 v[58:61], v28 offset:28672
	ds_read_b128 v[62:65], v28 offset:32768
	ds_read_b128 v[66:69], v28 offset:36864
	s_waitcnt vmcnt(28)
	s_waitcnt lgkmcnt(0)
; __device__ __forceinline__ void prologue(const Ctx& a, LAS unsigned char* lds, int wave_s) {
;     ...
;         for (int k = wave * 128; k < wave * 128 + 128; ++k) { const float w = W[(size_t)k * 6144];
; #pragma unroll
;             for (int b = 0; b < 10; ++b) acc[b] += cact[b * 1024 + k] * w; }
	v_fmac_f32_e32 v18, v100, v30
	v_fmac_f32_e32 v19, v100, v34
	v_fmac_f32_e32 v20, v100, v38
	v_fmac_f32_e32 v21, v100, v42
	v_fmac_f32_e32 v22, v100, v46
	v_fmac_f32_e32 v23, v100, v50
	v_fmac_f32_e32 v24, v100, v54
	v_fmac_f32_e32 v25, v100, v58
	v_fmac_f32_e32 v16, v100, v62
	v_fmac_f32_e32 v17, v100, v66
	v_fmac_f32_e32 v18, v101, v31
	v_fmac_f32_e32 v19, v101, v35
	v_fmac_f32_e32 v20, v101, v39
	v_fmac_f32_e32 v21, v101, v43
	v_fmac_f32_e32 v22, v101, v47
	v_fmac_f32_e32 v23, v101, v51
	v_fmac_f32_e32 v24, v101, v55
	v_fmac_f32_e32 v25, v101, v59
	v_fmac_f32_e32 v16, v101, v63
	v_fmac_f32_e32 v17, v101, v67
	v_fmac_f32_e32 v18, v102, v32
	v_fmac_f32_e32 v19, v102, v36
	v_fmac_f32_e32 v20, v102, v40
	v_fmac_f32_e32 v21, v102, v44
	v_fmac_f32_e32 v22, v102, v48
	v_fmac_f32_e32 v23, v102, v52
	v_fmac_f32_e32 v24, v102, v56
	v_fmac_f32_e32 v25, v102, v60
	v_fmac_f32_e32 v16, v102, v64
	v_fmac_f32_e32 v17, v102, v68
	v_fmac_f32_e32 v18, v103, v33
	v_fmac_f32_e32 v19, v103, v37
	v_fmac_f32_e32 v20, v103, v41
	v_fmac_f32_e32 v21, v103, v45
	v_fmac_f32_e32 v22, v103, v49
	v_fmac_f32_e32 v23, v103, v53
	v_fmac_f32_e32 v24, v103, v57
	v_fmac_f32_e32 v25, v103, v61
	v_fmac_f32_e32 v16, v103, v65
	v_fmac_f32_e32 v17, v103, v69
	v_mov_b32_e32 v28, s20
	s_add_i32 s20, s20, 16
	ds_read_b128 v[30:33], v28
	ds_read_b128 v[34:37], v28 offset:4096
	ds_read_b128 v[38:41], v28 offset:8192
	ds_read_b128 v[42:45], v28 offset:12288
	ds_read_b128 v[46:49], v28 offset:16384
	ds_read_b128 v[50:53], v28 offset:20480
	ds_read_b128 v[54:57], v28 offset:24576
	ds_read_b128 v[58:61], v28 offset:28672
	ds_read_b128 v[62:65], v28 offset:32768
	ds_read_b128 v[66:69], v28 offset:36864
	s_waitcnt vmcnt(24)
	s_waitcnt lgkmcnt(0)
	v_fmac_f32_e32 v18, v104, v30
	v_fmac_f32_e32 v19, v104, v34
	v_fmac_f32_e32 v20, v104, v38
	v_fmac_f32_e32 v21, v104, v42
	v_fmac_f32_e32 v22, v104, v46
	v_fmac_f32_e32 v23, v104, v50
	v_fmac_f32_e32 v24, v104, v54
	v_fmac_f32_e32 v25, v104, v58
	v_fmac_f32_e32 v16, v104, v62
	v_fmac_f32_e32 v17, v104, v66
	v_fmac_f32_e32 v18, v105, v31
	v_fmac_f32_e32 v19, v105, v35
	v_fmac_f32_e32 v20, v105, v39
	v_fmac_f32_e32 v21, v105, v43
	v_fmac_f32_e32 v22, v105, v47
	v_fmac_f32_e32 v23, v105, v51
	v_fmac_f32_e32 v24, v105, v55
	v_fmac_f32_e32 v25, v105, v59
	v_fmac_f32_e32 v16, v105, v63
	v_fmac_f32_e32 v17, v105, v67
	v_fmac_f32_e32 v18, v106, v32
	v_fmac_f32_e32 v19, v106, v36
	v_fmac_f32_e32 v20, v106, v40
	v_fmac_f32_e32 v21, v106, v44
	v_fmac_f32_e32 v22, v106, v48
	v_fmac_f32_e32 v23, v106, v52
	v_fmac_f32_e32 v24, v106, v56
	v_fmac_f32_e32 v25, v106, v60
	v_fmac_f32_e32 v16, v106, v64
	v_fmac_f32_e32 v17, v106, v68
	v_fmac_f32_e32 v18, v107, v33
	v_fmac_f32_e32 v19, v107, v37
	v_fmac_f32_e32 v20, v107, v41
	v_fmac_f32_e32 v21, v107, v45
	v_fmac_f32_e32 v22, v107, v49
	v_fmac_f32_e32 v23, v107, v53
	v_fmac_f32_e32 v24, v107, v57
	v_fmac_f32_e32 v25, v107, v61
	v_fmac_f32_e32 v16, v107, v65
	v_fmac_f32_e32 v17, v107, v69
	v_mov_b32_e32 v28, s20
	s_add_i32 s20, s20, 16
	ds_read_b128 v[30:33], v28
	ds_read_b128 v[34:37], v28 offset:4096
	ds_read_b128 v[38:41], v28 offset:8192
	ds_read_b128 v[42:45], v28 offset:12288
	ds_read_b128 v[46:49], v28 offset:16384
	ds_read_b128 v[50:53], v28 offset:20480
	ds_read_b128 v[54:57], v28 offset:24576
	ds_read_b128 v[58:61], v28 offset:28672
	ds_read_b128 v[62:65], v28 offset:32768
	ds_read_b128 v[66:69], v28 offset:36864
	s_waitcnt vmcnt(20)
	s_waitcnt lgkmcnt(0)
	v_fmac_f32_e32 v18, v108, v30
	v_fmac_f32_e32 v19, v108, v34
	v_fmac_f32_e32 v20, v108, v38
	v_fmac_f32_e32 v21, v108, v42
	v_fmac_f32_e32 v22, v108, v46
	v_fmac_f32_e32 v23, v108, v50
	v_fmac_f32_e32 v24, v108, v54
	v_fmac_f32_e32 v25, v108, v58
	v_fmac_f32_e32 v16, v108, v62
	v_fmac_f32_e32 v17, v108, v66
	v_fmac_f32_e32 v18, v109, v31
	v_fmac_f32_e32 v19, v109, v35
	v_fmac_f32_e32 v20, v109, v39
	v_fmac_f32_e32 v21, v109, v43
	v_fmac_f32_e32 v22, v109, v47
	v_fmac_f32_e32 v23, v109, v51
	v_fmac_f32_e32 v24, v109, v55
	v_fmac_f32_e32 v25, v109, v59
	v_fmac_f32_e32 v16, v109, v63
	v_fmac_f32_e32 v17, v109, v67
	v_fmac_f32_e32 v18, v110, v32
	v_fmac_f32_e32 v19, v110, v36
	v_fmac_f32_e32 v20, v110, v40
	v_fmac_f32_e32 v21, v110, v44
	v_fmac_f32_e32 v22, v110, v48
	v_fmac_f32_e32 v23, v110, v52
	v_fmac_f32_e32 v24, v110, v56
	v_fmac_f32_e32 v25, v110, v60
	v_fmac_f32_e32 v16, v110, v64
	v_fmac_f32_e32 v17, v110, v68
	v_fmac_f32_e32 v18, v111, v33
	v_fmac_f32_e32 v19, v111, v37
	v_fmac_f32_e32 v20, v111, v41
	v_fmac_f32_e32 v21, v111, v45
	v_fmac_f32_e32 v22, v111, v49
	v_fmac_f32_e32 v23, v111, v53
	v_fmac_f32_e32 v24, v111, v57
	v_fmac_f32_e32 v25, v111, v61
	v_fmac_f32_e32 v16, v111, v65
	v_fmac_f32_e32 v17, v111, v69
	v_mov_b32_e32 v28, s20
	s_add_i32 s20, s20, 16
	ds_read_b128 v[30:33], v28
	ds_read_b128 v[34:37], v28 offset:4096
	ds_read_b128 v[38:41], v28 offset:8192
	ds_read_b128 v[42:45], v28 offset:12288
	ds_read_b128 v[46:49], v28 offset:16384
	ds_read_b128 v[50:53], v28 offset:20480
	ds_read_b128 v[54:57], v28 offset:24576
	ds_read_b128 v[58:61], v28 offset:28672
	ds_read_b128 v[62:65], v28 offset:32768
	ds_read_b128 v[66:69], v28 offset:36864
	s_waitcnt vmcnt(16)
	s_waitcnt lgkmcnt(0)
; __device__ __forceinline__ void prologue(const Ctx& a, LAS unsigned char* lds, int wave_s) {
;     ...
;         for (int k = wave * 128; k < wave * 128 + 128; ++k) { const float w = W[(size_t)k * 6144];
; #pragma unroll
;             for (int b = 0; b < 10; ++b) acc[b] += cact[b * 1024 + k] * w; }
	v_fmac_f32_e32 v18, v112, v30
	v_fmac_f32_e32 v19, v112, v34
	v_fmac_f32_e32 v20, v112, v38
	v_fmac_f32_e32 v21, v112, v42
	v_fmac_f32_e32 v22, v112, v46
	v_fmac_f32_e32 v23, v112, v50
	v_fmac_f32_e32 v24, v112, v54
	v_fmac_f32_e32 v25, v112, v58
	v_fmac_f32_e32 v16, v112, v62
	v_fmac_f32_e32 v17, v112, v66
	v_fmac_f32_e32 v18, v113, v31
	v_fmac_f32_e32 v19, v113, v35
	v_fmac_f32_e32 v20, v113, v39
	v_fmac_f32_e32 v21, v113, v43
	v_fmac_f32_e32 v22, v113, v47
	v_fmac_f32_e32 v23, v113, v51
	v_fmac_f32_e32 v24, v113, v55
	v_fmac_f32_e32 v25, v113, v59
	v_fmac_f32_e32 v16, v113, v63
	v_fmac_f32_e32 v17, v113, v67
	v_fmac_f32_e32 v18, v114, v32
	v_fmac_f32_e32 v19, v114, v36
	v_fmac_f32_e32 v20, v114, v40
	v_fmac_f32_e32 v21, v114, v44
	v_fmac_f32_e32 v22, v114, v48
	v_fmac_f32_e32 v23, v114, v52
	v_fmac_f32_e32 v24, v114, v56
	v_fmac_f32_e32 v25, v114, v60
	v_fmac_f32_e32 v16, v114, v64
	v_fmac_f32_e32 v17, v114, v68
	v_fmac_f32_e32 v18, v115, v33
	v_fmac_f32_e32 v19, v115, v37
	v_fmac_f32_e32 v20, v115, v41
	v_fmac_f32_e32 v21, v115, v45
	v_fmac_f32_e32 v22, v115, v49
	v_fmac_f32_e32 v23, v115, v53
	v_fmac_f32_e32 v24, v115, v57
	v_fmac_f32_e32 v25, v115, v61
	v_fmac_f32_e32 v16, v115, v65
	v_fmac_f32_e32 v17, v115, v69
	v_mov_b32_e32 v28, s20
	s_add_i32 s20, s20, 16
	ds_read_b128 v[30:33], v28
	ds_read_b128 v[34:37], v28 offset:4096
	ds_read_b128 v[38:41], v28 offset:8192
	ds_read_b128 v[42:45], v28 offset:12288
	ds_read_b128 v[46:49], v28 offset:16384
	ds_read_b128 v[50:53], v28 offset:20480
	ds_read_b128 v[54:57], v28 offset:24576
	ds_read_b128 v[58:61], v28 offset:28672
	ds_read_b128 v[62:65], v28 offset:32768
	ds_read_b128 v[66:69], v28 offset:36864
	s_waitcnt vmcnt(12)
	s_waitcnt lgkmcnt(0)
	v_fmac_f32_e32 v18, v116, v30
	v_fmac_f32_e32 v19, v116, v34
	v_fmac_f32_e32 v20, v116, v38
	v_fmac_f32_e32 v21, v116, v42
	v_fmac_f32_e32 v22, v116, v46
	v_fmac_f32_e32 v23, v116, v50
	v_fmac_f32_e32 v24, v116, v54
	v_fmac_f32_e32 v25, v116, v58
	v_fmac_f32_e32 v16, v116, v62
	v_fmac_f32_e32 v17, v116, v66
	v_fmac_f32_e32 v18, v117, v31
	v_fmac_f32_e32 v19, v117, v35
	v_fmac_f32_e32 v20, v117, v39
	v_fmac_f32_e32 v21, v117, v43
	v_fmac_f32_e32 v22, v117, v47
	v_fmac_f32_e32 v23, v117, v51
	v_fmac_f32_e32 v24, v117, v55
	v_fmac_f32_e32 v25, v117, v59
	v_fmac_f32_e32 v16, v117, v63
	v_fmac_f32_e32 v17, v117, v67
	v_fmac_f32_e32 v18, v118, v32
	v_fmac_f32_e32 v19, v118, v36
	v_fmac_f32_e32 v20, v118, v40
	v_fmac_f32_e32 v21, v118, v44
	v_fmac_f32_e32 v22, v118, v48
	v_fmac_f32_e32 v23, v118, v52
	v_fmac_f32_e32 v24, v118, v56
	v_fmac_f32_e32 v25, v118, v60
	v_fmac_f32_e32 v16, v118, v64
	v_fmac_f32_e32 v17, v118, v68
	v_fmac_f32_e32 v18, v119, v33
	v_fmac_f32_e32 v19, v119, v37
	v_fmac_f32_e32 v20, v119, v41
	v_fmac_f32_e32 v21, v119, v45
	v_fmac_f32_e32 v22, v119, v49
	v_fmac_f32_e32 v23, v119, v53
	v_fmac_f32_e32 v24, v119, v57
	v_fmac_f32_e32 v25, v119, v61
	v_fmac_f32_e32 v16, v119, v65
	v_fmac_f32_e32 v17, v119, v69
	v_mov_b32_e32 v28, s20
	s_add_i32 s20, s20, 16
	ds_read_b128 v[30:33], v28
	ds_read_b128 v[34:37], v28 offset:4096
	ds_read_b128 v[38:41], v28 offset:8192
	ds_read_b128 v[42:45], v28 offset:12288
	ds_read_b128 v[46:49], v28 offset:16384
	ds_read_b128 v[50:53], v28 offset:20480
	ds_read_b128 v[54:57], v28 offset:24576
	ds_read_b128 v[58:61], v28 offset:28672
	ds_read_b128 v[62:65], v28 offset:32768
	ds_read_b128 v[66:69], v28 offset:36864
	s_waitcnt vmcnt(8)
	s_waitcnt lgkmcnt(0)
	v_fmac_f32_e32 v18, v120, v30
	v_fmac_f32_e32 v19, v120, v34
	v_fmac_f32_e32 v20, v120, v38
	v_fmac_f32_e32 v21, v120, v42
	v_fmac_f32_e32 v22, v120, v46
	v_fmac_f32_e32 v23, v120, v50
	v_fmac_f32_e32 v24, v120, v54
	v_fmac_f32_e32 v25, v120, v58
	v_fmac_f32_e32 v16, v120, v62
	v_fmac_f32_e32 v17, v120, v66
	v_fmac_f32_e32 v18, v121, v31
	v_fmac_f32_e32 v19, v121, v35
	v_fmac_f32_e32 v20, v121, v39
	v_fmac_f32_e32 v21, v121, v43
	v_fmac_f32_e32 v22, v121, v47
	v_fmac_f32_e32 v23, v121, v51
	v_fmac_f32_e32 v24, v121, v55
	v_fmac_f32_e32 v25, v121, v59
	v_fmac_f32_e32 v16, v121, v63
	v_fmac_f32_e32 v17, v121, v67
	v_fmac_f32_e32 v18, v122, v32
	v_fmac_f32_e32 v19, v122, v36
	v_fmac_f32_e32 v20, v122, v40
	v_fmac_f32_e32 v21, v122, v44
	v_fmac_f32_e32 v22, v122, v48
	v_fmac_f32_e32 v23, v122, v52
	v_fmac_f32_e32 v24, v122, v56
	v_fmac_f32_e32 v25, v122, v60
	v_fmac_f32_e32 v16, v122, v64
	v_fmac_f32_e32 v17, v122, v68
	v_fmac_f32_e32 v18, v123, v33
	v_fmac_f32_e32 v19, v123, v37
	v_fmac_f32_e32 v20, v123, v41
	v_fmac_f32_e32 v21, v123, v45
	v_fmac_f32_e32 v22, v123, v49
	v_fmac_f32_e32 v23, v123, v53
	v_fmac_f32_e32 v24, v123, v57
	v_fmac_f32_e32 v25, v123, v61
	v_fmac_f32_e32 v16, v123, v65
	v_fmac_f32_e32 v17, v123, v69
	v_mov_b32_e32 v28, s20
	s_add_i32 s20, s20, 16
	ds_read_b128 v[30:33], v28
	ds_read_b128 v[34:37], v28 offset:4096
	ds_read_b128 v[38:41], v28 offset:8192
	ds_read_b128 v[42:45], v28 offset:12288
	ds_read_b128 v[46:49], v28 offset:16384
	ds_read_b128 v[50:53], v28 offset:20480
	ds_read_b128 v[54:57], v28 offset:24576
	ds_read_b128 v[58:61], v28 offset:28672
	ds_read_b128 v[62:65], v28 offset:32768
	ds_read_b128 v[66:69], v28 offset:36864
	s_waitcnt vmcnt(4)
; __device__ __forceinline__ void prologue(const Ctx& a, LAS unsigned char* lds, int wave_s) {
;     ...
;         for (int k = wave * 128; k < wave * 128 + 128; ++k) { const float w = W[(size_t)k * 6144];
; #pragma unroll
;             for (int b = 0; b < 10; ++b) acc[b] += cact[b * 1024 + k] * w; }
; #pragma unroll
;         for (int b = 0; b < 10; ++b) red[(wave * 10 + b) * 64 + lane] = acc[b];
;         __syncthreads();
;         for (int i = tid; i < 640; i += NTHREADS) { const int b = i >> 6, l = i & 63; float s = 0.f;
	s_waitcnt lgkmcnt(0)
	v_fmac_f32_e32 v18, v124, v30
	v_fmac_f32_e32 v19, v124, v34
	v_fmac_f32_e32 v20, v124, v38
	v_fmac_f32_e32 v21, v124, v42
	v_fmac_f32_e32 v22, v124, v46
	v_fmac_f32_e32 v23, v124, v50
	v_fmac_f32_e32 v24, v124, v54
	v_fmac_f32_e32 v25, v124, v58
	v_fmac_f32_e32 v16, v124, v62
	v_fmac_f32_e32 v17, v124, v66
	v_fmac_f32_e32 v18, v125, v31
	v_fmac_f32_e32 v19, v125, v35
	v_fmac_f32_e32 v20, v125, v39
	v_fmac_f32_e32 v21, v125, v43
	v_fmac_f32_e32 v22, v125, v47
	v_fmac_f32_e32 v23, v125, v51
	v_fmac_f32_e32 v24, v125, v55
	v_fmac_f32_e32 v25, v125, v59
	v_fmac_f32_e32 v16, v125, v63
	v_fmac_f32_e32 v17, v125, v67
	v_fmac_f32_e32 v18, v126, v32
	v_fmac_f32_e32 v19, v126, v36
	v_fmac_f32_e32 v20, v126, v40
	v_fmac_f32_e32 v21, v126, v44
	v_fmac_f32_e32 v22, v126, v48
	v_fmac_f32_e32 v23, v126, v52
	v_fmac_f32_e32 v24, v126, v56
	v_fmac_f32_e32 v25, v126, v60
	v_fmac_f32_e32 v16, v126, v64
	v_fmac_f32_e32 v17, v126, v68
	v_fmac_f32_e32 v18, v127, v33
	v_fmac_f32_e32 v19, v127, v37
	v_fmac_f32_e32 v20, v127, v41
	v_fmac_f32_e32 v21, v127, v45
	v_fmac_f32_e32 v22, v127, v49
	v_fmac_f32_e32 v23, v127, v53
	v_fmac_f32_e32 v24, v127, v57
	v_fmac_f32_e32 v25, v127, v61
	v_fmac_f32_e32 v16, v127, v65
	v_fmac_f32_e32 v17, v127, v69
	v_mov_b32_e32 v28, s20
	s_add_i32 s20, s20, 16
	ds_read_b128 v[30:33], v28
	ds_read_b128 v[34:37], v28 offset:4096
	ds_read_b128 v[38:41], v28 offset:8192
	ds_read_b128 v[42:45], v28 offset:12288
	ds_read_b128 v[46:49], v28 offset:16384
	ds_read_b128 v[50:53], v28 offset:20480
	ds_read_b128 v[54:57], v28 offset:24576
	ds_read_b128 v[58:61], v28 offset:28672
	ds_read_b128 v[62:65], v28 offset:32768
	ds_read_b128 v[66:69], v28 offset:36864
	s_waitcnt vmcnt(0)
	s_waitcnt lgkmcnt(0)
	v_fmac_f32_e32 v18, v128, v30
	v_fmac_f32_e32 v19, v128, v34
	v_fmac_f32_e32 v20, v128, v38
	v_fmac_f32_e32 v21, v128, v42
	v_fmac_f32_e32 v22, v128, v46
	v_fmac_f32_e32 v23, v128, v50
	v_fmac_f32_e32 v24, v128, v54
	v_fmac_f32_e32 v25, v128, v58
	v_fmac_f32_e32 v16, v128, v62
	v_fmac_f32_e32 v17, v128, v66
	v_fmac_f32_e32 v18, v129, v31
	v_fmac_f32_e32 v19, v129, v35
	v_fmac_f32_e32 v20, v129, v39
	v_fmac_f32_e32 v21, v129, v43
	v_fmac_f32_e32 v22, v129, v47
	v_fmac_f32_e32 v23, v129, v51
	v_fmac_f32_e32 v24, v129, v55
	v_fmac_f32_e32 v25, v129, v59
	v_fmac_f32_e32 v16, v129, v63
	v_fmac_f32_e32 v17, v129, v67
	v_fmac_f32_e32 v18, v130, v32
	v_fmac_f32_e32 v19, v130, v36
	v_fmac_f32_e32 v20, v130, v40
	v_fmac_f32_e32 v21, v130, v44
	v_fmac_f32_e32 v22, v130, v48
	v_fmac_f32_e32 v23, v130, v52
	v_fmac_f32_e32 v24, v130, v56
	v_fmac_f32_e32 v25, v130, v60
	v_fmac_f32_e32 v16, v130, v64
	v_fmac_f32_e32 v17, v130, v68
	v_fmac_f32_e32 v18, v131, v33
	v_fmac_f32_e32 v19, v131, v37
	v_fmac_f32_e32 v20, v131, v41
	v_fmac_f32_e32 v21, v131, v45
	v_fmac_f32_e32 v22, v131, v49
	v_fmac_f32_e32 v23, v131, v53
	v_fmac_f32_e32 v24, v131, v57
	v_fmac_f32_e32 v25, v131, v61
	v_fmac_f32_e32 v16, v131, v65
	v_fmac_f32_e32 v17, v131, v69
	s_cmp_eq_u32 s10, 0x300000
	s_cbranch_scc0 .LBB0_27
	ds_write2st64_b32 v7, v18, v19 offset0:160 offset1:161
	ds_write2st64_b32 v7, v20, v21 offset0:162 offset1:163
	ds_write2st64_b32 v7, v22, v23 offset0:164 offset1:165
	ds_write2st64_b32 v7, v24, v25 offset0:166 offset1:167
	ds_write2st64_b32 v7, v16, v17 offset0:168 offset1:169
	s_waitcnt lgkmcnt(0)
	s_barrier
	s_and_saveexec_b64 s[10:11], vcc
	s_cbranch_execz .LBB0_25
	v_mov_b32_e32 v8, s15
	ds_read_b64 v[14:15], v8
	s_mul_i32 s0, s19, 0x1800
	s_add_i32 s0, s0, s6
	v_or_b32_e32 v16, s0, v1
	s_mul_i32 s19, s19, 10
	v_ashrrev_i32_e32 v17, 31, v16
	v_lshl_add_u64 v[18:19], s[6:7], 2, v[10:11]
	s_mov_b64 s[6:7], 0
	v_mov_b32_e32 v8, v4
